# A-in / D-in epilogues: __shfl_xor(v,16|32) expansions (index arithmetic + ds_bpermute LDS round trip) replaced by v_permlane16/32_swap butterflies where the shuffle only feeds v + shfl_xor(v,K) under
# baseline (speedup 1.0000x reference)
; DI unsigned pk2(float a, float b) { f32x2 v = {a, b}; bf16v2_t r = __builtin_convertvector(v, bf16v2_t); return __builtin_bit_cast(unsigned, r); }
;     DI void operator()(const Acc& acc, const Unit& u, int wr, int wc, int fr, int fq, const float (&pre)[8]) const {
;     ...
;             for (int m = 0; m < 4; ++m) { bf16_t* rowp = O + (size_t)(row0 + ai * HALF + m * 16) * 8192 + col0;
;                 f32x4 v[2][2]; const float rs = rsqrtf(pre[ai * 4 + m] * (1.f / DM) + EPS);
; #pragma unroll
;                 for (int bj = 0; bj < 2; ++bj) { v[bj][0] = acc[ai][bj][m][0] * rs; v[bj][1] = acc[ai][bj][m][1] * rs; }
;                 if (nrm) { float ss = 0.f;
; #pragma unroll
;                     for (int bj = 0; bj < 2; ++bj)
; #pragma unroll
;                         for (int n = 0; n < 2; ++n) ss += v[bj][n][0] * v[bj][n][0] + v[bj][n][1] * v[bj][n][1] + v[bj][n][2] * v[bj][n][2] + v[bj][n][3] * v[bj][n][3];
;                     ss += __shfl_xor(ss, 16); ss += __shfl_xor(ss, 32);
;                     const float sc = rsqrtf(ss * (1.f / 64.f) + EPS);
; #pragma unroll
;                     for (int bj = 0; bj < 2; ++bj) { v[bj][0] = v[bj][0] * sc * gn[bj][0]; v[bj][1] = v[bj][1] * sc * gn[bj][1]; } }
; #pragma unroll
;                 for (int bj = 0; bj < 2; ++bj) { u32x4 w; w.x = pk2(v[bj][0][0], v[bj][0][1]); w.y = pk2(v[bj][0][2], v[bj][0][3]); w.z = pk2(v[bj][1][0], v[bj][1][1]); w.w = pk2(v[bj][1][2], v[bj][1][3]);
;                     *(u32x4*)(rowp + 32 * bj) = w; } }
.LBB0_152:
	s_waitcnt vmcnt(0) lgkmcnt(0)
	v_fmamk_f32 v162, v162, 0x3a000000, v172
	v_mul_f32_e32 v163, 0x4b800000, v162
	v_cmp_gt_f32_e32 vcc, s73, v162
	s_nop 1
	v_cndmask_b32_e32 v162, v162, v163, vcc
	v_rsq_f32_e32 v162, v162
	s_nop 0
	v_mul_f32_e32 v163, 0x45800000, v162
	v_cndmask_b32_e32 v164, v162, v163, vcc
	v_pk_mul_f32 v[162:163], v[164:165], v[116:117] op_sel_hi:[0,1]
	v_pk_mul_f32 v[116:117], v[164:165], v[114:115] op_sel_hi:[0,1]
	v_cndmask_b32_e64 v114, 0, 1, s[52:53]
	v_pk_mul_f32 v[126:127], v[164:165], v[126:127] op_sel_hi:[0,1]
	v_pk_mul_f32 v[124:125], v[164:165], v[124:125] op_sel_hi:[0,1]
	v_pk_mul_f32 v[122:123], v[164:165], v[122:123] op_sel_hi:[0,1]
	v_pk_mul_f32 v[120:121], v[164:165], v[120:121] op_sel_hi:[0,1]
	v_pk_mul_f32 v[118:119], v[164:165], v[118:119] op_sel_hi:[0,1]
	v_cmp_ne_u32_e64 s[6:7], 1, v114
	s_andn2_b64 vcc, exec, s[52:53]
	v_pk_mul_f32 v[164:165], v[164:165], v[112:113] op_sel_hi:[0,1]
	s_cbranch_vccnz .LBB0_154
	v_mov_b32_e32 v114, v121
	v_mov_b32_e32 v115, v125
	v_mov_b32_e32 v112, v120
	v_mov_b32_e32 v113, v124
	v_pk_mul_f32 v[114:115], v[114:115], v[114:115]
	v_mov_b32_e32 v184, v165
	v_pk_fma_f32 v[112:113], v[112:113], v[112:113], v[114:115]
	v_mov_b32_e32 v114, v122
	v_mov_b32_e32 v115, v126
	v_pk_fma_f32 v[112:113], v[114:115], v[114:115], v[112:113]
	v_mov_b32_e32 v114, v123
	v_mov_b32_e32 v115, v127
	v_mov_b32_e32 v185, v163
	v_pk_fma_f32 v[112:113], v[114:115], v[114:115], v[112:113]
	v_mov_b32_e32 v114, v164
	v_mov_b32_e32 v115, v162
	v_pk_mul_f32 v[184:185], v[184:185], v[184:185]
	v_add_f32_e32 v112, v112, v113
	v_pk_fma_f32 v[114:115], v[114:115], v[114:115], v[184:185]
	v_mov_b32_e32 v184, v116
	v_mov_b32_e32 v185, v118
	v_pk_fma_f32 v[114:115], v[184:185], v[184:185], v[114:115]
	v_mov_b32_e32 v184, v117
	v_mov_b32_e32 v185, v119
	v_pk_fma_f32 v[114:115], v[184:185], v[184:185], v[114:115]
	v_xor_b32_e32 v113, 16, v174
	v_add_f32_e32 v112, v115, v112
	v_add_f32_e32 v112, v114, v112
	v_and_b32_e32 v114, 64, v174
	v_add_u32_e32 v114, 64, v114
	v_cmp_lt_i32_e32 vcc, v113, v114
	s_nop 1
	v_cndmask_b32_e32 v113, v174, v113, vcc
	v_lshlrev_b32_e32 v113, 2, v113
	v_mov_b32_e32 v113, v112
	s_nop 1
	v_permlane16_swap_b32_e32 v113, v112
	s_waitcnt lgkmcnt(0)
	v_add_f32_e32 v112, v112, v113
	v_xor_b32_e32 v113, 32, v174
	v_cmp_lt_i32_e32 vcc, v113, v114
	s_nop 1
	v_cndmask_b32_e32 v113, v174, v113, vcc
	v_lshlrev_b32_e32 v113, 2, v113
	v_mov_b32_e32 v113, v112
	s_nop 1
	v_permlane32_swap_b32_e32 v113, v112
	s_waitcnt lgkmcnt(0)
	v_add_f32_e32 v112, v112, v113
	v_fmamk_f32 v112, v112, 0x3c800000, v172
	v_mul_f32_e32 v113, 0x4b800000, v112
	v_cmp_gt_f32_e32 vcc, s73, v112
	s_nop 1
	v_cndmask_b32_e32 v112, v112, v113, vcc
	v_rsq_f32_e32 v112, v112
	s_nop 0
	v_mul_f32_e32 v113, 0x45800000, v112
	v_cndmask_b32_e32 v112, v112, v113, vcc
	v_pk_mul_f32 v[114:115], v[124:125], v[112:113] op_sel_hi:[1,0]
	v_pk_mul_f32 v[124:125], v[126:127], v[112:113] op_sel_hi:[1,0]
	v_pk_mul_f32 v[118:119], v[118:119], v[112:113] op_sel_hi:[1,0]
	v_pk_mul_f32 v[126:127], v[160:161], v[124:125]
	v_pk_mul_f32 v[124:125], v[158:159], v[114:115]
	v_pk_mul_f32 v[114:115], v[120:121], v[112:113] op_sel_hi:[1,0]
	v_pk_mul_f32 v[120:121], v[122:123], v[112:113] op_sel_hi:[1,0]
	v_pk_mul_f32 v[118:119], v[152:153], v[118:119]
	v_pk_mul_f32 v[122:123], v[156:157], v[120:121]
	v_pk_mul_f32 v[120:121], v[154:155], v[114:115]
	v_pk_mul_f32 v[114:115], v[162:163], v[112:113] op_sel_hi:[1,0]
	s_nop 0
	v_pk_mul_f32 v[162:163], v[150:151], v[114:115]
	v_pk_mul_f32 v[114:115], v[164:165], v[112:113] op_sel_hi:[1,0]
	v_pk_mul_f32 v[112:113], v[116:117], v[112:113] op_sel_hi:[1,0]
	v_pk_mul_f32 v[164:165], v[146:147], v[114:115]
	v_pk_mul_f32 v[116:117], v[148:149], v[112:113]
.LBB0_154:
	v_cvt_pk_bf16_f32 v124, v124, v125
	v_cvt_pk_bf16_f32 v125, v126, v127
	v_cvt_pk_bf16_f32 v126, v120, v121
	v_cvt_pk_bf16_f32 v121, v118, v119
	v_fmamk_f32 v118, v183, 0x3a000000, v172
	v_mul_f32_e32 v119, 0x4b800000, v118
	v_cmp_gt_f32_e32 vcc, s73, v118
	v_lshl_add_u32 v114, s50, 8, v166
	v_ashrrev_i32_e32 v115, 31, v114
	v_cndmask_b32_e32 v118, v118, v119, vcc
	v_rsq_f32_e32 v118, v118
	v_lshl_or_b32 v112, s80, 8, v168
	v_lshlrev_b64 v[184:185], 14, v[114:115]
	v_cvt_pk_bf16_f32 v127, v122, v123
	v_cvt_pk_bf16_f32 v123, v116, v117
	v_mul_f32_e32 v116, 0x45800000, v118
	v_ashrrev_i32_e32 v113, 31, v112
	v_lshl_add_u64 v[184:185], s[16:17], 0, v[184:185]
	v_cndmask_b32_e32 v116, v118, v116, vcc
	v_lshl_add_u64 v[184:185], v[112:113], 1, v[184:185]
	v_cvt_pk_bf16_f32 v120, v162, v163
	v_cvt_pk_bf16_f32 v122, v164, v165
	v_pk_mul_f32 v[110:111], v[116:117], v[110:111] op_sel_hi:[0,1]
	v_pk_mul_f32 v[108:109], v[116:117], v[108:109] op_sel_hi:[0,1]
	v_pk_mul_f32 v[106:107], v[116:117], v[106:107] op_sel_hi:[0,1]
	v_pk_mul_f32 v[104:105], v[116:117], v[104:105] op_sel_hi:[0,1]
	v_pk_mul_f32 v[102:103], v[116:117], v[102:103] op_sel_hi:[0,1]
	v_pk_mul_f32 v[100:101], v[116:117], v[100:101] op_sel_hi:[0,1]
	v_pk_mul_f32 v[98:99], v[116:117], v[98:99] op_sel_hi:[0,1]
	s_and_b64 vcc, exec, s[6:7]
	v_pk_mul_f32 v[96:97], v[116:117], v[96:97] op_sel_hi:[0,1]
	flat_store_dwordx4 v[184:185], v[124:127]
	flat_store_dwordx4 v[184:185], v[120:123] offset:64
	s_cbranch_vccnz .LBB0_156
; DI unsigned pk2(float a, float b) { f32x2 v = {a, b}; bf16v2_t r = __builtin_convertvector(v, bf16v2_t); return __builtin_bit_cast(unsigned, r); }
;     DI void operator()(const Acc& acc, const Unit& u, int wr, int wc, int fr, int fq, const float (&pre)[8]) const {
;     ...
;             for (int m = 0; m < 4; ++m) { bf16_t* rowp = O + (size_t)(row0 + ai * HALF + m * 16) * 8192 + col0;
;                 f32x4 v[2][2]; const float rs = rsqrtf(pre[ai * 4 + m] * (1.f / DM) + EPS);
; #pragma unroll
;                 for (int bj = 0; bj < 2; ++bj) { v[bj][0] = acc[ai][bj][m][0] * rs; v[bj][1] = acc[ai][bj][m][1] * rs; }
;                 if (nrm) { float ss = 0.f;
; #pragma unroll
;                     for (int bj = 0; bj < 2; ++bj)
; #pragma unroll
;                         for (int n = 0; n < 2; ++n) ss += v[bj][n][0] * v[bj][n][0] + v[bj][n][1] * v[bj][n][1] + v[bj][n][2] * v[bj][n][2] + v[bj][n][3] * v[bj][n][3];
;                     ss += __shfl_xor(ss, 16); ss += __shfl_xor(ss, 32);
;                     const float sc = rsqrtf(ss * (1.f / 64.f) + EPS);
; #pragma unroll
;                     for (int bj = 0; bj < 2; ++bj) { v[bj][0] = v[bj][0] * sc * gn[bj][0]; v[bj][1] = v[bj][1] * sc * gn[bj][1]; } }
; #pragma unroll
;                 for (int bj = 0; bj < 2; ++bj) { u32x4 w; w.x = pk2(v[bj][0][0], v[bj][0][1]); w.y = pk2(v[bj][0][2], v[bj][0][3]); w.z = pk2(v[bj][1][0], v[bj][1][1]); w.w = pk2(v[bj][1][2], v[bj][1][3]);
;                     *(u32x4*)(rowp + 32 * bj) = w; } }
	v_mov_b32_e32 v118, v105
	v_mov_b32_e32 v119, v109
	v_mov_b32_e32 v116, v104
	v_mov_b32_e32 v117, v108
	v_pk_mul_f32 v[118:119], v[118:119], v[118:119]
	v_mov_b32_e32 v120, v97
	v_pk_fma_f32 v[116:117], v[116:117], v[116:117], v[118:119]
	v_mov_b32_e32 v118, v106
	v_mov_b32_e32 v119, v110
	v_pk_fma_f32 v[116:117], v[118:119], v[118:119], v[116:117]
	v_mov_b32_e32 v118, v107
	v_mov_b32_e32 v119, v111
	v_mov_b32_e32 v121, v101
	v_pk_fma_f32 v[116:117], v[118:119], v[118:119], v[116:117]
	v_mov_b32_e32 v118, v96
	v_mov_b32_e32 v119, v100
	v_pk_mul_f32 v[120:121], v[120:121], v[120:121]
	v_add_f32_e32 v116, v116, v117
	v_pk_fma_f32 v[118:119], v[118:119], v[118:119], v[120:121]
	v_mov_b32_e32 v120, v98
	v_mov_b32_e32 v121, v102
	v_pk_fma_f32 v[118:119], v[120:121], v[120:121], v[118:119]
	v_mov_b32_e32 v120, v99
	v_mov_b32_e32 v121, v103
	v_pk_fma_f32 v[118:119], v[120:121], v[120:121], v[118:119]
	v_xor_b32_e32 v117, 16, v174
	v_add_f32_e32 v116, v119, v116
	v_add_f32_e32 v116, v118, v116
	v_and_b32_e32 v118, 64, v174
	v_add_u32_e32 v118, 64, v118
	v_cmp_lt_i32_e32 vcc, v117, v118
	s_nop 1
	v_cndmask_b32_e32 v117, v174, v117, vcc
	v_lshlrev_b32_e32 v117, 2, v117
	v_mov_b32_e32 v117, v116
	s_nop 1
	v_permlane16_swap_b32_e32 v117, v116
	s_waitcnt lgkmcnt(0)
	v_add_f32_e32 v116, v116, v117
	v_xor_b32_e32 v117, 32, v174
	v_cmp_lt_i32_e32 vcc, v117, v118
	s_nop 1
	v_cndmask_b32_e32 v117, v174, v117, vcc
	v_lshlrev_b32_e32 v117, 2, v117
	v_mov_b32_e32 v117, v116
	s_nop 1
	v_permlane32_swap_b32_e32 v117, v116
	s_waitcnt lgkmcnt(0)
	v_add_f32_e32 v116, v116, v117
	v_fmamk_f32 v116, v116, 0x3c800000, v172
	v_mul_f32_e32 v117, 0x4b800000, v116
	v_cmp_gt_f32_e32 vcc, s73, v116
	s_nop 1
	v_cndmask_b32_e32 v116, v116, v117, vcc
	v_rsq_f32_e32 v116, v116
	s_nop 0
	v_mul_f32_e32 v117, 0x45800000, v116
	v_cndmask_b32_e32 v116, v116, v117, vcc
	v_pk_mul_f32 v[108:109], v[108:109], v[116:117] op_sel_hi:[1,0]
	v_pk_mul_f32 v[110:111], v[110:111], v[116:117] op_sel_hi:[1,0]
	v_pk_mul_f32 v[104:105], v[104:105], v[116:117] op_sel_hi:[1,0]
	v_pk_mul_f32 v[106:107], v[106:107], v[116:117] op_sel_hi:[1,0]
	v_pk_mul_f32 v[100:101], v[100:101], v[116:117] op_sel_hi:[1,0]
	v_pk_mul_f32 v[102:103], v[102:103], v[116:117] op_sel_hi:[1,0]
	v_pk_mul_f32 v[96:97], v[96:97], v[116:117] op_sel_hi:[1,0]
	v_pk_mul_f32 v[98:99], v[98:99], v[116:117] op_sel_hi:[1,0]
	v_pk_mul_f32 v[110:111], v[160:161], v[110:111]
	v_pk_mul_f32 v[108:109], v[158:159], v[108:109]
	v_pk_mul_f32 v[106:107], v[156:157], v[106:107]
	v_pk_mul_f32 v[104:105], v[154:155], v[104:105]
	v_pk_mul_f32 v[102:103], v[152:153], v[102:103]
	v_pk_mul_f32 v[100:101], v[150:151], v[100:101]
	v_pk_mul_f32 v[98:99], v[148:149], v[98:99]
	v_pk_mul_f32 v[96:97], v[146:147], v[96:97]
.LBB0_156:
	v_cvt_pk_bf16_f32 v100, v100, v101
	v_cvt_pk_bf16_f32 v101, v102, v103
	v_fmamk_f32 v102, v182, 0x3a000000, v172
	v_mul_f32_e32 v103, 0x4b800000, v102
	v_cmp_gt_f32_e32 vcc, s73, v102
	v_cvt_pk_bf16_f32 v108, v108, v109
	v_cvt_pk_bf16_f32 v109, v110, v111
	v_cndmask_b32_e32 v102, v102, v103, vcc
	v_cvt_pk_bf16_f32 v110, v104, v105
	v_rsq_f32_e32 v104, v102
	v_or_b32_e32 v116, 16, v114
	v_ashrrev_i32_e32 v117, 31, v116
	v_lshlrev_b64 v[116:117], 14, v[116:117]
	v_cvt_pk_bf16_f32 v102, v96, v97
	v_mul_f32_e32 v96, 0x45800000, v104
	v_lshl_add_u64 v[116:117], s[16:17], 0, v[116:117]
	v_cndmask_b32_e32 v96, v104, v96, vcc
	v_lshl_add_u64 v[116:117], v[112:113], 1, v[116:117]
	v_cvt_pk_bf16_f32 v111, v106, v107
	v_cvt_pk_bf16_f32 v103, v98, v99
	v_pk_mul_f32 v[94:95], v[96:97], v[94:95] op_sel_hi:[0,1]
	v_pk_mul_f32 v[92:93], v[96:97], v[92:93] op_sel_hi:[0,1]
	v_pk_mul_f32 v[90:91], v[96:97], v[90:91] op_sel_hi:[0,1]
	v_pk_mul_f32 v[88:89], v[96:97], v[88:89] op_sel_hi:[0,1]
	v_pk_mul_f32 v[86:87], v[96:97], v[86:87] op_sel_hi:[0,1]
	v_pk_mul_f32 v[84:85], v[96:97], v[84:85] op_sel_hi:[0,1]
	v_pk_mul_f32 v[82:83], v[96:97], v[82:83] op_sel_hi:[0,1]
	s_and_b64 vcc, exec, s[6:7]
	v_pk_mul_f32 v[80:81], v[96:97], v[80:81] op_sel_hi:[0,1]
	flat_store_dwordx4 v[116:117], v[108:111]
	flat_store_dwordx4 v[116:117], v[100:103] offset:64
	s_cbranch_vccnz .LBB0_158
	v_mov_b32_e32 v98, v89
	v_mov_b32_e32 v99, v93
	v_mov_b32_e32 v96, v88
	v_mov_b32_e32 v97, v92
	v_pk_mul_f32 v[98:99], v[98:99], v[98:99]
	v_mov_b32_e32 v100, v81
	v_pk_fma_f32 v[96:97], v[96:97], v[96:97], v[98:99]
	v_mov_b32_e32 v98, v90
	v_mov_b32_e32 v99, v94
	v_pk_fma_f32 v[96:97], v[98:99], v[98:99], v[96:97]
	v_mov_b32_e32 v98, v91
	v_mov_b32_e32 v99, v95
	v_mov_b32_e32 v101, v85
	v_pk_fma_f32 v[96:97], v[98:99], v[98:99], v[96:97]
	v_mov_b32_e32 v98, v80
	v_mov_b32_e32 v99, v84
	v_pk_mul_f32 v[100:101], v[100:101], v[100:101]
	v_add_f32_e32 v96, v96, v97
	v_pk_fma_f32 v[98:99], v[98:99], v[98:99], v[100:101]
	v_mov_b32_e32 v100, v82
	v_mov_b32_e32 v101, v86
	v_pk_fma_f32 v[98:99], v[100:101], v[100:101], v[98:99]
	v_mov_b32_e32 v100, v83
	v_mov_b32_e32 v101, v87
	v_pk_fma_f32 v[98:99], v[100:101], v[100:101], v[98:99]
	v_xor_b32_e32 v97, 16, v174
	v_add_f32_e32 v96, v99, v96
	v_add_f32_e32 v96, v98, v96
	v_and_b32_e32 v98, 64, v174
	v_add_u32_e32 v98, 64, v98
	v_cmp_lt_i32_e32 vcc, v97, v98
	s_nop 1
	v_cndmask_b32_e32 v97, v174, v97, vcc
	v_lshlrev_b32_e32 v97, 2, v97
	v_mov_b32_e32 v97, v96
	s_nop 1
	v_permlane16_swap_b32_e32 v97, v96
	s_waitcnt lgkmcnt(0)
	v_add_f32_e32 v96, v96, v97
	v_xor_b32_e32 v97, 32, v174
	v_cmp_lt_i32_e32 vcc, v97, v98
	s_nop 1
	v_cndmask_b32_e32 v97, v174, v97, vcc
	v_lshlrev_b32_e32 v97, 2, v97
	v_mov_b32_e32 v97, v96
	s_nop 1
	v_permlane32_swap_b32_e32 v97, v96
	s_waitcnt lgkmcnt(0)
	v_add_f32_e32 v96, v96, v97
	v_fmamk_f32 v96, v96, 0x3c800000, v172
	v_mul_f32_e32 v97, 0x4b800000, v96
	v_cmp_gt_f32_e32 vcc, s73, v96
	s_nop 1
	v_cndmask_b32_e32 v96, v96, v97, vcc
	v_rsq_f32_e32 v96, v96
	s_nop 0
	v_mul_f32_e32 v97, 0x45800000, v96
	v_cndmask_b32_e32 v96, v96, v97, vcc
	v_pk_mul_f32 v[92:93], v[92:93], v[96:97] op_sel_hi:[1,0]
	v_pk_mul_f32 v[94:95], v[94:95], v[96:97] op_sel_hi:[1,0]
	v_pk_mul_f32 v[88:89], v[88:89], v[96:97] op_sel_hi:[1,0]
	v_pk_mul_f32 v[90:91], v[90:91], v[96:97] op_sel_hi:[1,0]
	v_pk_mul_f32 v[84:85], v[84:85], v[96:97] op_sel_hi:[1,0]
	v_pk_mul_f32 v[86:87], v[86:87], v[96:97] op_sel_hi:[1,0]
	v_pk_mul_f32 v[80:81], v[80:81], v[96:97] op_sel_hi:[1,0]
	v_pk_mul_f32 v[82:83], v[82:83], v[96:97] op_sel_hi:[1,0]
	v_pk_mul_f32 v[94:95], v[160:161], v[94:95]
	v_pk_mul_f32 v[92:93], v[158:159], v[92:93]
	v_pk_mul_f32 v[90:91], v[156:157], v[90:91]
	v_pk_mul_f32 v[88:89], v[154:155], v[88:89]
	v_pk_mul_f32 v[86:87], v[152:153], v[86:87]
	v_pk_mul_f32 v[84:85], v[150:151], v[84:85]
	v_pk_mul_f32 v[82:83], v[148:149], v[82:83]
	v_pk_mul_f32 v[80:81], v[146:147], v[80:81]
; DI unsigned pk2(float a, float b) { f32x2 v = {a, b}; bf16v2_t r = __builtin_convertvector(v, bf16v2_t); return __builtin_bit_cast(unsigned, r); }
;     DI void operator()(const Acc& acc, const Unit& u, int wr, int wc, int fr, int fq, const float (&pre)[8]) const {
;     ...
;             for (int m = 0; m < 4; ++m) { bf16_t* rowp = O + (size_t)(row0 + ai * HALF + m * 16) * 8192 + col0;
;                 f32x4 v[2][2]; const float rs = rsqrtf(pre[ai * 4 + m] * (1.f / DM) + EPS);
; #pragma unroll
;                 for (int bj = 0; bj < 2; ++bj) { v[bj][0] = acc[ai][bj][m][0] * rs; v[bj][1] = acc[ai][bj][m][1] * rs; }
;                 if (nrm) { float ss = 0.f;
; #pragma unroll
;                     for (int bj = 0; bj < 2; ++bj)
; #pragma unroll
;                         for (int n = 0; n < 2; ++n) ss += v[bj][n][0] * v[bj][n][0] + v[bj][n][1] * v[bj][n][1] + v[bj][n][2] * v[bj][n][2] + v[bj][n][3] * v[bj][n][3];
;                     ss += __shfl_xor(ss, 16); ss += __shfl_xor(ss, 32);
;                     const float sc = rsqrtf(ss * (1.f / 64.f) + EPS);
; #pragma unroll
;                     for (int bj = 0; bj < 2; ++bj) { v[bj][0] = v[bj][0] * sc * gn[bj][0]; v[bj][1] = v[bj][1] * sc * gn[bj][1]; } }
; #pragma unroll
;                 for (int bj = 0; bj < 2; ++bj) { u32x4 w; w.x = pk2(v[bj][0][0], v[bj][0][1]); w.y = pk2(v[bj][0][2], v[bj][0][3]); w.z = pk2(v[bj][1][0], v[bj][1][1]); w.w = pk2(v[bj][1][2], v[bj][1][3]);
;                     *(u32x4*)(rowp + 32 * bj) = w; } }
.LBB0_158:
	v_cvt_pk_bf16_f32 v84, v84, v85
	v_cvt_pk_bf16_f32 v85, v86, v87
	v_fmamk_f32 v86, v180, 0x3a000000, v172
	v_mul_f32_e32 v87, 0x4b800000, v86
	v_cmp_gt_f32_e32 vcc, s73, v86
	v_cvt_pk_bf16_f32 v92, v92, v93
	v_cvt_pk_bf16_f32 v93, v94, v95
	v_cndmask_b32_e32 v86, v86, v87, vcc
	v_cvt_pk_bf16_f32 v94, v88, v89
	v_rsq_f32_e32 v88, v86
	v_or_b32_e32 v96, 32, v114
	v_ashrrev_i32_e32 v97, 31, v96
	v_lshlrev_b64 v[96:97], 14, v[96:97]
	v_cvt_pk_bf16_f32 v86, v80, v81
	v_mul_f32_e32 v80, 0x45800000, v88
	v_lshl_add_u64 v[96:97], s[16:17], 0, v[96:97]
	v_cndmask_b32_e32 v80, v88, v80, vcc
	v_lshl_add_u64 v[96:97], v[112:113], 1, v[96:97]
	v_cvt_pk_bf16_f32 v95, v90, v91
	v_cvt_pk_bf16_f32 v87, v82, v83
	v_pk_mul_f32 v[78:79], v[80:81], v[78:79] op_sel_hi:[0,1]
	v_pk_mul_f32 v[76:77], v[80:81], v[76:77] op_sel_hi:[0,1]
	v_pk_mul_f32 v[74:75], v[80:81], v[74:75] op_sel_hi:[0,1]
	v_pk_mul_f32 v[72:73], v[80:81], v[72:73] op_sel_hi:[0,1]
	v_pk_mul_f32 v[70:71], v[80:81], v[70:71] op_sel_hi:[0,1]
	v_pk_mul_f32 v[68:69], v[80:81], v[68:69] op_sel_hi:[0,1]
	v_pk_mul_f32 v[66:67], v[80:81], v[66:67] op_sel_hi:[0,1]
	s_and_b64 vcc, exec, s[6:7]
	v_pk_mul_f32 v[64:65], v[80:81], v[64:65] op_sel_hi:[0,1]
	flat_store_dwordx4 v[96:97], v[92:95]
	flat_store_dwordx4 v[96:97], v[84:87] offset:64
	s_cbranch_vccnz .LBB0_160
	v_mov_b32_e32 v82, v73
	v_mov_b32_e32 v83, v77
	v_mov_b32_e32 v80, v72
	v_mov_b32_e32 v81, v76
	v_pk_mul_f32 v[82:83], v[82:83], v[82:83]
	v_mov_b32_e32 v84, v65
	v_pk_fma_f32 v[80:81], v[80:81], v[80:81], v[82:83]
	v_mov_b32_e32 v82, v74
	v_mov_b32_e32 v83, v78
	v_pk_fma_f32 v[80:81], v[82:83], v[82:83], v[80:81]
	v_mov_b32_e32 v82, v75
	v_mov_b32_e32 v83, v79
	v_mov_b32_e32 v85, v69
	v_pk_fma_f32 v[80:81], v[82:83], v[82:83], v[80:81]
	v_mov_b32_e32 v82, v64
	v_mov_b32_e32 v83, v68
	v_pk_mul_f32 v[84:85], v[84:85], v[84:85]
	v_add_f32_e32 v80, v80, v81
	v_pk_fma_f32 v[82:83], v[82:83], v[82:83], v[84:85]
	v_mov_b32_e32 v84, v66
	v_mov_b32_e32 v85, v70
	v_pk_fma_f32 v[82:83], v[84:85], v[84:85], v[82:83]
	v_mov_b32_e32 v84, v67
	v_mov_b32_e32 v85, v71
	v_pk_fma_f32 v[82:83], v[84:85], v[84:85], v[82:83]
	v_xor_b32_e32 v81, 16, v174
	v_add_f32_e32 v80, v83, v80
	v_add_f32_e32 v80, v82, v80
	v_and_b32_e32 v82, 64, v174
	v_add_u32_e32 v82, 64, v82
	v_cmp_lt_i32_e32 vcc, v81, v82
	s_nop 1
	v_cndmask_b32_e32 v81, v174, v81, vcc
	v_lshlrev_b32_e32 v81, 2, v81
	v_mov_b32_e32 v81, v80
	s_nop 1
	v_permlane16_swap_b32_e32 v81, v80
	s_waitcnt lgkmcnt(0)
	v_add_f32_e32 v80, v80, v81
	v_xor_b32_e32 v81, 32, v174
	v_cmp_lt_i32_e32 vcc, v81, v82
	s_nop 1
	v_cndmask_b32_e32 v81, v174, v81, vcc
	v_lshlrev_b32_e32 v81, 2, v81
	v_mov_b32_e32 v81, v80
	s_nop 1
	v_permlane32_swap_b32_e32 v81, v80
	s_waitcnt lgkmcnt(0)
	v_add_f32_e32 v80, v80, v81
	v_fmamk_f32 v80, v80, 0x3c800000, v172
	v_mul_f32_e32 v81, 0x4b800000, v80
	v_cmp_gt_f32_e32 vcc, s73, v80
	s_nop 1
	v_cndmask_b32_e32 v80, v80, v81, vcc
	v_rsq_f32_e32 v80, v80
	s_nop 0
	v_mul_f32_e32 v81, 0x45800000, v80
	v_cndmask_b32_e32 v80, v80, v81, vcc
	v_pk_mul_f32 v[76:77], v[76:77], v[80:81] op_sel_hi:[1,0]
	v_pk_mul_f32 v[78:79], v[78:79], v[80:81] op_sel_hi:[1,0]
	v_pk_mul_f32 v[72:73], v[72:73], v[80:81] op_sel_hi:[1,0]
	v_pk_mul_f32 v[74:75], v[74:75], v[80:81] op_sel_hi:[1,0]
	v_pk_mul_f32 v[68:69], v[68:69], v[80:81] op_sel_hi:[1,0]
	v_pk_mul_f32 v[70:71], v[70:71], v[80:81] op_sel_hi:[1,0]
	v_pk_mul_f32 v[64:65], v[64:65], v[80:81] op_sel_hi:[1,0]
	v_pk_mul_f32 v[66:67], v[66:67], v[80:81] op_sel_hi:[1,0]
	v_pk_mul_f32 v[78:79], v[160:161], v[78:79]
	v_pk_mul_f32 v[76:77], v[158:159], v[76:77]
	v_pk_mul_f32 v[74:75], v[156:157], v[74:75]
	v_pk_mul_f32 v[72:73], v[154:155], v[72:73]
	v_pk_mul_f32 v[70:71], v[152:153], v[70:71]
	v_pk_mul_f32 v[68:69], v[150:151], v[68:69]
	v_pk_mul_f32 v[66:67], v[148:149], v[66:67]
	v_pk_mul_f32 v[64:65], v[146:147], v[64:65]
.LBB0_160:
	v_cvt_pk_bf16_f32 v68, v68, v69
	v_cvt_pk_bf16_f32 v69, v70, v71
	v_fmamk_f32 v70, v179, 0x3a000000, v172
	v_mul_f32_e32 v71, 0x4b800000, v70
	v_cmp_gt_f32_e32 vcc, s73, v70
	v_cvt_pk_bf16_f32 v76, v76, v77
	v_cvt_pk_bf16_f32 v77, v78, v79
	v_cndmask_b32_e32 v70, v70, v71, vcc
	v_cvt_pk_bf16_f32 v78, v72, v73
	v_rsq_f32_e32 v72, v70
	v_or_b32_e32 v80, 48, v114
	v_ashrrev_i32_e32 v81, 31, v80
	v_lshlrev_b64 v[80:81], 14, v[80:81]
	v_cvt_pk_bf16_f32 v70, v64, v65
	v_mul_f32_e32 v64, 0x45800000, v72
	v_lshl_add_u64 v[80:81], s[16:17], 0, v[80:81]
	v_cvt_pk_bf16_f32 v71, v66, v67
	v_cndmask_b32_e32 v66, v72, v64, vcc
	v_lshl_add_u64 v[80:81], v[112:113], 1, v[80:81]
	v_cvt_pk_bf16_f32 v79, v74, v75
	v_pk_mul_f32 v[62:63], v[66:67], v[62:63] op_sel_hi:[0,1]
	v_pk_mul_f32 v[60:61], v[66:67], v[60:61] op_sel_hi:[0,1]
	v_pk_mul_f32 v[58:59], v[66:67], v[58:59] op_sel_hi:[0,1]
	v_pk_mul_f32 v[64:65], v[66:67], v[56:57] op_sel_hi:[0,1]
	v_pk_mul_f32 v[54:55], v[66:67], v[54:55] op_sel_hi:[0,1]
	v_pk_mul_f32 v[56:57], v[66:67], v[52:53] op_sel_hi:[0,1]
	v_pk_mul_f32 v[50:51], v[66:67], v[50:51] op_sel_hi:[0,1]
	s_and_b64 vcc, exec, s[6:7]
	v_pk_mul_f32 v[52:53], v[66:67], v[48:49] op_sel_hi:[0,1]
	flat_store_dwordx4 v[80:81], v[76:79]
	flat_store_dwordx4 v[80:81], v[68:71] offset:64
	s_cbranch_vccnz .LBB0_162
; DI unsigned pk2(float a, float b) { f32x2 v = {a, b}; bf16v2_t r = __builtin_convertvector(v, bf16v2_t); return __builtin_bit_cast(unsigned, r); }
;     DI void operator()(const Acc& acc, const Unit& u, int wr, int wc, int fr, int fq, const float (&pre)[8]) const {
;     ...
;             for (int m = 0; m < 4; ++m) { bf16_t* rowp = O + (size_t)(row0 + ai * HALF + m * 16) * 8192 + col0;
;                 f32x4 v[2][2]; const float rs = rsqrtf(pre[ai * 4 + m] * (1.f / DM) + EPS);
; #pragma unroll
;                 for (int bj = 0; bj < 2; ++bj) { v[bj][0] = acc[ai][bj][m][0] * rs; v[bj][1] = acc[ai][bj][m][1] * rs; }
;                 if (nrm) { float ss = 0.f;
; #pragma unroll
;                     for (int bj = 0; bj < 2; ++bj)
; #pragma unroll
;                         for (int n = 0; n < 2; ++n) ss += v[bj][n][0] * v[bj][n][0] + v[bj][n][1] * v[bj][n][1] + v[bj][n][2] * v[bj][n][2] + v[bj][n][3] * v[bj][n][3];
;                     ss += __shfl_xor(ss, 16); ss += __shfl_xor(ss, 32);
;                     const float sc = rsqrtf(ss * (1.f / 64.f) + EPS);
; #pragma unroll
;                     for (int bj = 0; bj < 2; ++bj) { v[bj][0] = v[bj][0] * sc * gn[bj][0]; v[bj][1] = v[bj][1] * sc * gn[bj][1]; } }
; #pragma unroll
;                 for (int bj = 0; bj < 2; ++bj) { u32x4 w; w.x = pk2(v[bj][0][0], v[bj][0][1]); w.y = pk2(v[bj][0][2], v[bj][0][3]); w.z = pk2(v[bj][1][0], v[bj][1][1]); w.w = pk2(v[bj][1][2], v[bj][1][3]);
;                     *(u32x4*)(rowp + 32 * bj) = w; } }
	v_mov_b32_e32 v66, v65
	v_mov_b32_e32 v67, v61
	v_mov_b32_e32 v48, v64
	v_mov_b32_e32 v49, v60
	v_pk_mul_f32 v[66:67], v[66:67], v[66:67]
	v_mov_b32_e32 v68, v53
	v_pk_fma_f32 v[48:49], v[48:49], v[48:49], v[66:67]
	v_mov_b32_e32 v66, v58
	v_mov_b32_e32 v67, v62
	v_pk_fma_f32 v[48:49], v[66:67], v[66:67], v[48:49]
	v_mov_b32_e32 v66, v59
	v_mov_b32_e32 v67, v63
	v_mov_b32_e32 v69, v57
	v_pk_fma_f32 v[48:49], v[66:67], v[66:67], v[48:49]
	v_mov_b32_e32 v66, v52
	v_mov_b32_e32 v67, v56
	v_pk_mul_f32 v[68:69], v[68:69], v[68:69]
	v_add_f32_e32 v48, v48, v49
	v_pk_fma_f32 v[66:67], v[66:67], v[66:67], v[68:69]
	v_mov_b32_e32 v68, v50
	v_mov_b32_e32 v69, v54
	v_pk_fma_f32 v[66:67], v[68:69], v[68:69], v[66:67]
	v_mov_b32_e32 v68, v51
	v_mov_b32_e32 v69, v55
	v_pk_fma_f32 v[66:67], v[68:69], v[68:69], v[66:67]
	v_xor_b32_e32 v49, 16, v174
	v_add_f32_e32 v48, v67, v48
	v_add_f32_e32 v48, v66, v48
	v_and_b32_e32 v66, 64, v174
	v_add_u32_e32 v66, 64, v66
	v_cmp_lt_i32_e32 vcc, v49, v66
	s_nop 1
	v_cndmask_b32_e32 v49, v174, v49, vcc
	v_lshlrev_b32_e32 v49, 2, v49
	v_mov_b32_e32 v49, v48
	s_nop 1
	v_permlane16_swap_b32_e32 v49, v48
	s_waitcnt lgkmcnt(0)
	v_add_f32_e32 v48, v48, v49
	v_xor_b32_e32 v49, 32, v174
	v_cmp_lt_i32_e32 vcc, v49, v66
	s_nop 1
	v_cndmask_b32_e32 v49, v174, v49, vcc
	v_lshlrev_b32_e32 v49, 2, v49
	v_mov_b32_e32 v49, v48
	s_nop 1
	v_permlane32_swap_b32_e32 v49, v48
	s_waitcnt lgkmcnt(0)
	v_add_f32_e32 v48, v48, v49
	v_fmamk_f32 v48, v48, 0x3c800000, v172
	v_mul_f32_e32 v49, 0x4b800000, v48
	v_cmp_gt_f32_e32 vcc, s73, v48
	s_nop 1
	v_cndmask_b32_e32 v48, v48, v49, vcc
	v_rsq_f32_e32 v48, v48
	s_nop 0
	v_mul_f32_e32 v49, 0x45800000, v48
	v_cndmask_b32_e32 v48, v48, v49, vcc
	v_pk_mul_f32 v[60:61], v[60:61], v[48:49] op_sel_hi:[1,0]
	v_pk_mul_f32 v[62:63], v[62:63], v[48:49] op_sel_hi:[1,0]
	v_pk_mul_f32 v[64:65], v[64:65], v[48:49] op_sel_hi:[1,0]
	v_pk_mul_f32 v[58:59], v[58:59], v[48:49] op_sel_hi:[1,0]
	v_pk_mul_f32 v[56:57], v[56:57], v[48:49] op_sel_hi:[1,0]
	v_pk_mul_f32 v[54:55], v[54:55], v[48:49] op_sel_hi:[1,0]
	v_pk_mul_f32 v[52:53], v[52:53], v[48:49] op_sel_hi:[1,0]
	v_pk_mul_f32 v[48:49], v[50:51], v[48:49] op_sel_hi:[1,0]
	v_pk_mul_f32 v[62:63], v[160:161], v[62:63]
	v_pk_mul_f32 v[60:61], v[158:159], v[60:61]
	v_pk_mul_f32 v[58:59], v[156:157], v[58:59]
	v_pk_mul_f32 v[64:65], v[154:155], v[64:65]
	v_pk_mul_f32 v[54:55], v[152:153], v[54:55]
	v_pk_mul_f32 v[56:57], v[150:151], v[56:57]
	v_pk_mul_f32 v[50:51], v[148:149], v[48:49]
	v_pk_mul_f32 v[52:53], v[146:147], v[52:53]
.LBB0_162:
	v_lshlrev_b64 v[48:49], 14, v[114:115]
	v_lshl_add_u64 v[48:49], s[16:17], 0, v[48:49]
	v_lshl_add_u64 v[48:49], v[112:113], 1, v[48:49]
	v_cvt_pk_bf16_f32 v60, v60, v61
	v_cvt_pk_bf16_f32 v61, v62, v63
	v_cvt_pk_bf16_f32 v63, v58, v59
	v_add_co_u32_e32 v58, vcc, s74, v48
	v_cvt_pk_bf16_f32 v56, v56, v57
	s_nop 0
	v_addc_co_u32_e32 v59, vcc, 0, v49, vcc
	v_cvt_pk_bf16_f32 v57, v54, v55
	v_fmamk_f32 v54, v177, 0x3a000000, v172
	v_mul_f32_e32 v55, 0x4b800000, v54
	v_cmp_gt_f32_e32 vcc, s73, v54
	v_cvt_pk_bf16_f32 v62, v64, v65
	flat_store_dwordx4 v[58:59], v[60:63]
	v_cndmask_b32_e32 v54, v54, v55, vcc
	v_rsq_f32_e32 v54, v54
	v_cvt_pk_bf16_f32 v59, v50, v51
	v_lshl_add_u64 v[66:67], v[48:49], 0, s[30:31]
	v_cvt_pk_bf16_f32 v58, v52, v53
	v_mul_f32_e32 v50, 0x45800000, v54
	v_cndmask_b32_e32 v50, v54, v50, vcc
	v_pk_mul_f32 v[46:47], v[50:51], v[46:47] op_sel_hi:[0,1]
	v_pk_mul_f32 v[44:45], v[50:51], v[44:45] op_sel_hi:[0,1]
	v_pk_mul_f32 v[42:43], v[50:51], v[42:43] op_sel_hi:[0,1]
	v_pk_mul_f32 v[40:41], v[50:51], v[40:41] op_sel_hi:[0,1]
	v_pk_mul_f32 v[38:39], v[50:51], v[38:39] op_sel_hi:[0,1]
	v_pk_mul_f32 v[36:37], v[50:51], v[36:37] op_sel_hi:[0,1]
	v_pk_mul_f32 v[34:35], v[50:51], v[34:35] op_sel_hi:[0,1]
	s_and_b64 vcc, exec, s[6:7]
	v_pk_mul_f32 v[32:33], v[50:51], v[32:33] op_sel_hi:[0,1]
	flat_store_dwordx4 v[66:67], v[56:59] offset:64
	s_cbranch_vccnz .LBB0_164
	v_mov_b32_e32 v52, v41
	v_mov_b32_e32 v53, v45
	v_mov_b32_e32 v50, v40
	v_mov_b32_e32 v51, v44
	v_pk_mul_f32 v[52:53], v[52:53], v[52:53]
	v_mov_b32_e32 v54, v33
	v_pk_fma_f32 v[50:51], v[50:51], v[50:51], v[52:53]
	v_mov_b32_e32 v52, v42
	v_mov_b32_e32 v53, v46
	v_pk_fma_f32 v[50:51], v[52:53], v[52:53], v[50:51]
	v_mov_b32_e32 v52, v43
	v_mov_b32_e32 v53, v47
	v_mov_b32_e32 v55, v37
	v_pk_fma_f32 v[50:51], v[52:53], v[52:53], v[50:51]
	v_mov_b32_e32 v52, v32
	v_mov_b32_e32 v53, v36
	v_pk_mul_f32 v[54:55], v[54:55], v[54:55]
	v_add_f32_e32 v50, v50, v51
	v_pk_fma_f32 v[52:53], v[52:53], v[52:53], v[54:55]
	v_mov_b32_e32 v54, v34
	v_mov_b32_e32 v55, v38
	v_pk_fma_f32 v[52:53], v[54:55], v[54:55], v[52:53]
	v_mov_b32_e32 v54, v35
	v_mov_b32_e32 v55, v39
	v_pk_fma_f32 v[52:53], v[54:55], v[54:55], v[52:53]
	v_xor_b32_e32 v51, 16, v174
	v_add_f32_e32 v50, v53, v50
	v_add_f32_e32 v50, v52, v50
	v_and_b32_e32 v52, 64, v174
	v_add_u32_e32 v52, 64, v52
	v_cmp_lt_i32_e32 vcc, v51, v52
	s_nop 1
	v_cndmask_b32_e32 v51, v174, v51, vcc
	v_lshlrev_b32_e32 v51, 2, v51
	v_mov_b32_e32 v51, v50
	s_nop 1
	v_permlane16_swap_b32_e32 v51, v50
	s_waitcnt lgkmcnt(0)
	v_add_f32_e32 v50, v50, v51
	v_xor_b32_e32 v51, 32, v174
	v_cmp_lt_i32_e32 vcc, v51, v52
	s_nop 1
	v_cndmask_b32_e32 v51, v174, v51, vcc
	v_lshlrev_b32_e32 v51, 2, v51
	v_mov_b32_e32 v51, v50
	s_nop 1
	v_permlane32_swap_b32_e32 v51, v50
	s_waitcnt lgkmcnt(0)
	v_add_f32_e32 v50, v50, v51
	v_fmamk_f32 v50, v50, 0x3c800000, v172
	v_mul_f32_e32 v51, 0x4b800000, v50
	v_cmp_gt_f32_e32 vcc, s73, v50
	s_nop 1
	v_cndmask_b32_e32 v50, v50, v51, vcc
	v_rsq_f32_e32 v50, v50
	s_nop 0
	v_mul_f32_e32 v51, 0x45800000, v50
	v_cndmask_b32_e32 v50, v50, v51, vcc
	v_pk_mul_f32 v[44:45], v[44:45], v[50:51] op_sel_hi:[1,0]
	v_pk_mul_f32 v[46:47], v[46:47], v[50:51] op_sel_hi:[1,0]
	v_pk_mul_f32 v[40:41], v[40:41], v[50:51] op_sel_hi:[1,0]
	v_pk_mul_f32 v[42:43], v[42:43], v[50:51] op_sel_hi:[1,0]
	v_pk_mul_f32 v[36:37], v[36:37], v[50:51] op_sel_hi:[1,0]
	v_pk_mul_f32 v[38:39], v[38:39], v[50:51] op_sel_hi:[1,0]
	v_pk_mul_f32 v[32:33], v[32:33], v[50:51] op_sel_hi:[1,0]
	v_pk_mul_f32 v[34:35], v[34:35], v[50:51] op_sel_hi:[1,0]
	v_pk_mul_f32 v[46:47], v[160:161], v[46:47]
	v_pk_mul_f32 v[44:45], v[158:159], v[44:45]
	v_pk_mul_f32 v[42:43], v[156:157], v[42:43]
	v_pk_mul_f32 v[40:41], v[154:155], v[40:41]
	v_pk_mul_f32 v[38:39], v[152:153], v[38:39]
	v_pk_mul_f32 v[36:37], v[150:151], v[36:37]
	v_pk_mul_f32 v[34:35], v[148:149], v[34:35]
	v_pk_mul_f32 v[32:33], v[146:147], v[32:33]
; DI unsigned pk2(float a, float b) { f32x2 v = {a, b}; bf16v2_t r = __builtin_convertvector(v, bf16v2_t); return __builtin_bit_cast(unsigned, r); }
;     DI void operator()(const Acc& acc, const Unit& u, int wr, int wc, int fr, int fq, const float (&pre)[8]) const {
;     ...
;             for (int m = 0; m < 4; ++m) { bf16_t* rowp = O + (size_t)(row0 + ai * HALF + m * 16) * 8192 + col0;
;                 f32x4 v[2][2]; const float rs = rsqrtf(pre[ai * 4 + m] * (1.f / DM) + EPS);
; #pragma unroll
;                 for (int bj = 0; bj < 2; ++bj) { v[bj][0] = acc[ai][bj][m][0] * rs; v[bj][1] = acc[ai][bj][m][1] * rs; }
;                 if (nrm) { float ss = 0.f;
; #pragma unroll
;                     for (int bj = 0; bj < 2; ++bj)
; #pragma unroll
;                         for (int n = 0; n < 2; ++n) ss += v[bj][n][0] * v[bj][n][0] + v[bj][n][1] * v[bj][n][1] + v[bj][n][2] * v[bj][n][2] + v[bj][n][3] * v[bj][n][3];
;                     ss += __shfl_xor(ss, 16); ss += __shfl_xor(ss, 32);
;                     const float sc = rsqrtf(ss * (1.f / 64.f) + EPS);
; #pragma unroll
;                     for (int bj = 0; bj < 2; ++bj) { v[bj][0] = v[bj][0] * sc * gn[bj][0]; v[bj][1] = v[bj][1] * sc * gn[bj][1]; } }
; #pragma unroll
;                 for (int bj = 0; bj < 2; ++bj) { u32x4 w; w.x = pk2(v[bj][0][0], v[bj][0][1]); w.y = pk2(v[bj][0][2], v[bj][0][3]); w.z = pk2(v[bj][1][0], v[bj][1][1]); w.w = pk2(v[bj][1][2], v[bj][1][3]);
;                     *(u32x4*)(rowp + 32 * bj) = w; } }
.LBB0_164:
	v_cvt_pk_bf16_f32 v44, v44, v45
	v_cvt_pk_bf16_f32 v45, v46, v47
	v_cvt_pk_bf16_f32 v46, v40, v41
	v_add_co_u32_e32 v40, vcc, s75, v48
	v_cvt_pk_bf16_f32 v36, v36, v37
	s_nop 0
	v_addc_co_u32_e32 v41, vcc, 0, v49, vcc
	v_cvt_pk_bf16_f32 v37, v38, v39
	v_fmamk_f32 v38, v176, 0x3a000000, v172
	v_mul_f32_e32 v39, 0x4b800000, v38
	v_cmp_gt_f32_e32 vcc, s73, v38
	v_cvt_pk_bf16_f32 v47, v42, v43
	flat_store_dwordx4 v[40:41], v[44:47]
	v_cndmask_b32_e32 v38, v38, v39, vcc
	v_rsq_f32_e32 v40, v38
	v_cvt_pk_bf16_f32 v38, v32, v33
	v_cvt_pk_bf16_f32 v39, v34, v35
	v_lshl_add_u64 v[50:51], v[48:49], 0, s[34:35]
	v_mul_f32_e32 v32, 0x45800000, v40
	v_cndmask_b32_e32 v34, v40, v32, vcc
	v_pk_mul_f32 v[30:31], v[34:35], v[30:31] op_sel_hi:[0,1]
	v_pk_mul_f32 v[28:29], v[34:35], v[28:29] op_sel_hi:[0,1]
	v_pk_mul_f32 v[26:27], v[34:35], v[26:27] op_sel_hi:[0,1]
	v_pk_mul_f32 v[32:33], v[34:35], v[24:25] op_sel_hi:[0,1]
	v_pk_mul_f32 v[22:23], v[34:35], v[22:23] op_sel_hi:[0,1]
	v_pk_mul_f32 v[24:25], v[34:35], v[20:21] op_sel_hi:[0,1]
	v_pk_mul_f32 v[18:19], v[34:35], v[18:19] op_sel_hi:[0,1]
	s_and_b64 vcc, exec, s[6:7]
	v_pk_mul_f32 v[20:21], v[34:35], v[16:17] op_sel_hi:[0,1]
	flat_store_dwordx4 v[50:51], v[36:39] offset:64
	s_cbranch_vccnz .LBB0_166
	v_mov_b32_e32 v34, v33
	v_mov_b32_e32 v35, v29
	v_mov_b32_e32 v16, v32
	v_mov_b32_e32 v17, v28
	v_pk_mul_f32 v[34:35], v[34:35], v[34:35]
	v_mov_b32_e32 v36, v21
	v_pk_fma_f32 v[16:17], v[16:17], v[16:17], v[34:35]
	v_mov_b32_e32 v34, v26
	v_mov_b32_e32 v35, v30
	v_pk_fma_f32 v[16:17], v[34:35], v[34:35], v[16:17]
	v_mov_b32_e32 v34, v27
	v_mov_b32_e32 v35, v31
	v_mov_b32_e32 v37, v25
	v_pk_fma_f32 v[16:17], v[34:35], v[34:35], v[16:17]
	v_mov_b32_e32 v34, v20
	v_mov_b32_e32 v35, v24
	v_pk_mul_f32 v[36:37], v[36:37], v[36:37]
	v_add_f32_e32 v16, v16, v17
	v_pk_fma_f32 v[34:35], v[34:35], v[34:35], v[36:37]
	v_mov_b32_e32 v36, v18
	v_mov_b32_e32 v37, v22
	v_pk_fma_f32 v[34:35], v[36:37], v[36:37], v[34:35]
	v_mov_b32_e32 v36, v19
	v_mov_b32_e32 v37, v23
	v_pk_fma_f32 v[34:35], v[36:37], v[36:37], v[34:35]
	v_xor_b32_e32 v17, 16, v174
	v_add_f32_e32 v16, v35, v16
	v_add_f32_e32 v16, v34, v16
	v_and_b32_e32 v34, 64, v174
	v_add_u32_e32 v34, 64, v34
	v_cmp_lt_i32_e32 vcc, v17, v34
	s_nop 1
	v_cndmask_b32_e32 v17, v174, v17, vcc
	v_lshlrev_b32_e32 v17, 2, v17
	v_mov_b32_e32 v17, v16
	s_nop 1
	v_permlane16_swap_b32_e32 v17, v16
	s_waitcnt lgkmcnt(0)
	v_add_f32_e32 v16, v16, v17
	v_xor_b32_e32 v17, 32, v174
	v_cmp_lt_i32_e32 vcc, v17, v34
	s_nop 1
	v_cndmask_b32_e32 v17, v174, v17, vcc
	v_lshlrev_b32_e32 v17, 2, v17
	v_mov_b32_e32 v17, v16
	s_nop 1
	v_permlane32_swap_b32_e32 v17, v16
	s_waitcnt lgkmcnt(0)
	v_add_f32_e32 v16, v16, v17
	v_fmamk_f32 v16, v16, 0x3c800000, v172
	v_mul_f32_e32 v17, 0x4b800000, v16
	v_cmp_gt_f32_e32 vcc, s73, v16
	s_nop 1
	v_cndmask_b32_e32 v16, v16, v17, vcc
	v_rsq_f32_e32 v16, v16
	s_nop 0
	v_mul_f32_e32 v17, 0x45800000, v16
	v_cndmask_b32_e32 v16, v16, v17, vcc
	v_pk_mul_f32 v[28:29], v[28:29], v[16:17] op_sel_hi:[1,0]
	v_pk_mul_f32 v[30:31], v[30:31], v[16:17] op_sel_hi:[1,0]
	v_pk_mul_f32 v[32:33], v[32:33], v[16:17] op_sel_hi:[1,0]
	v_pk_mul_f32 v[26:27], v[26:27], v[16:17] op_sel_hi:[1,0]
	v_pk_mul_f32 v[24:25], v[24:25], v[16:17] op_sel_hi:[1,0]
	v_pk_mul_f32 v[22:23], v[22:23], v[16:17] op_sel_hi:[1,0]
	v_pk_mul_f32 v[20:21], v[20:21], v[16:17] op_sel_hi:[1,0]
	v_pk_mul_f32 v[16:17], v[18:19], v[16:17] op_sel_hi:[1,0]
	v_pk_mul_f32 v[30:31], v[160:161], v[30:31]
	v_pk_mul_f32 v[28:29], v[158:159], v[28:29]
	v_pk_mul_f32 v[26:27], v[156:157], v[26:27]
	v_pk_mul_f32 v[32:33], v[154:155], v[32:33]
	v_pk_mul_f32 v[22:23], v[152:153], v[22:23]
	v_pk_mul_f32 v[24:25], v[150:151], v[24:25]
	v_pk_mul_f32 v[18:19], v[148:149], v[16:17]
	v_pk_mul_f32 v[20:21], v[146:147], v[20:21]
; DI unsigned pk2(float a, float b) { f32x2 v = {a, b}; bf16v2_t r = __builtin_convertvector(v, bf16v2_t); return __builtin_bit_cast(unsigned, r); }
;     DI void operator()(const Acc& acc, const Unit& u, int wr, int wc, int fr, int fq, const float (&pre)[8]) const {
;     ...
;             for (int m = 0; m < 4; ++m) { bf16_t* rowp = O + (size_t)(row0 + ai * HALF + m * 16) * 8192 + col0;
;                 f32x4 v[2][2]; const float rs = rsqrtf(pre[ai * 4 + m] * (1.f / DM) + EPS);
; #pragma unroll
;                 for (int bj = 0; bj < 2; ++bj) { v[bj][0] = acc[ai][bj][m][0] * rs; v[bj][1] = acc[ai][bj][m][1] * rs; }
;                 if (nrm) { float ss = 0.f;
; #pragma unroll
;                     for (int bj = 0; bj < 2; ++bj)
; #pragma unroll
;                         for (int n = 0; n < 2; ++n) ss += v[bj][n][0] * v[bj][n][0] + v[bj][n][1] * v[bj][n][1] + v[bj][n][2] * v[bj][n][2] + v[bj][n][3] * v[bj][n][3];
;                     ss += __shfl_xor(ss, 16); ss += __shfl_xor(ss, 32);
;                     const float sc = rsqrtf(ss * (1.f / 64.f) + EPS);
; #pragma unroll
;                     for (int bj = 0; bj < 2; ++bj) { v[bj][0] = v[bj][0] * sc * gn[bj][0]; v[bj][1] = v[bj][1] * sc * gn[bj][1]; } }
; #pragma unroll
;                 for (int bj = 0; bj < 2; ++bj) { u32x4 w; w.x = pk2(v[bj][0][0], v[bj][0][1]); w.y = pk2(v[bj][0][2], v[bj][0][3]); w.z = pk2(v[bj][1][0], v[bj][1][1]); w.w = pk2(v[bj][1][2], v[bj][1][3]);
;                     *(u32x4*)(rowp + 32 * bj) = w; } }
.LBB0_166:
	v_lshlrev_b64 v[16:17], 14, v[114:115]
	v_lshl_add_u64 v[16:17], s[16:17], 0, v[16:17]
	v_lshl_add_u64 v[16:17], v[112:113], 1, v[16:17]
	v_cvt_pk_bf16_f32 v28, v28, v29
	v_cvt_pk_bf16_f32 v29, v30, v31
	v_cvt_pk_bf16_f32 v31, v26, v27
	v_add_co_u32_e32 v26, vcc, s76, v16
	v_cvt_pk_bf16_f32 v24, v24, v25
	s_nop 0
	v_addc_co_u32_e32 v27, vcc, 0, v17, vcc
	v_cvt_pk_bf16_f32 v25, v22, v23
	v_fmamk_f32 v22, v175, 0x3a000000, v172
	v_mul_f32_e32 v23, 0x4b800000, v22
	v_cmp_gt_f32_e32 vcc, s73, v22
	v_cvt_pk_bf16_f32 v30, v32, v33
	flat_store_dwordx4 v[26:27], v[28:31]
	v_cndmask_b32_e32 v22, v22, v23, vcc
	v_rsq_f32_e32 v22, v22
	v_cvt_pk_bf16_f32 v27, v18, v19
	v_lshl_add_u64 v[34:35], v[16:17], 0, s[36:37]
	v_cvt_pk_bf16_f32 v26, v20, v21
	v_mul_f32_e32 v18, 0x45800000, v22
	v_cndmask_b32_e32 v18, v22, v18, vcc
	v_pk_mul_f32 v[14:15], v[18:19], v[14:15] op_sel_hi:[0,1]
	v_pk_mul_f32 v[12:13], v[18:19], v[12:13] op_sel_hi:[0,1]
	v_pk_mul_f32 v[10:11], v[18:19], v[10:11] op_sel_hi:[0,1]
	v_pk_mul_f32 v[8:9], v[18:19], v[8:9] op_sel_hi:[0,1]
	v_pk_mul_f32 v[6:7], v[18:19], v[6:7] op_sel_hi:[0,1]
	v_pk_mul_f32 v[4:5], v[18:19], v[4:5] op_sel_hi:[0,1]
	v_pk_mul_f32 v[2:3], v[18:19], v[2:3] op_sel_hi:[0,1]
	s_and_b64 vcc, exec, s[6:7]
	v_pk_mul_f32 v[0:1], v[18:19], v[0:1] op_sel_hi:[0,1]
	flat_store_dwordx4 v[34:35], v[24:27] offset:64
	s_cbranch_vccnz .LBB0_168
	v_mov_b32_e32 v20, v9
	v_mov_b32_e32 v21, v13
	v_mov_b32_e32 v18, v8
	v_mov_b32_e32 v19, v12
	v_pk_mul_f32 v[20:21], v[20:21], v[20:21]
	v_mov_b32_e32 v22, v1
	v_pk_fma_f32 v[18:19], v[18:19], v[18:19], v[20:21]
	v_mov_b32_e32 v20, v10
	v_mov_b32_e32 v21, v14
	v_pk_fma_f32 v[18:19], v[20:21], v[20:21], v[18:19]
	v_mov_b32_e32 v20, v11
	v_mov_b32_e32 v21, v15
	v_mov_b32_e32 v23, v5
	v_pk_fma_f32 v[18:19], v[20:21], v[20:21], v[18:19]
	v_mov_b32_e32 v20, v0
	v_mov_b32_e32 v21, v4
	v_pk_mul_f32 v[22:23], v[22:23], v[22:23]
	v_add_f32_e32 v18, v18, v19
	v_pk_fma_f32 v[20:21], v[20:21], v[20:21], v[22:23]
	v_mov_b32_e32 v22, v2
	v_mov_b32_e32 v23, v6
	v_pk_fma_f32 v[20:21], v[22:23], v[22:23], v[20:21]
	v_mov_b32_e32 v22, v3
	v_mov_b32_e32 v23, v7
	v_pk_fma_f32 v[20:21], v[22:23], v[22:23], v[20:21]
	v_xor_b32_e32 v19, 16, v174
	v_add_f32_e32 v18, v21, v18
	v_add_f32_e32 v18, v20, v18
	v_and_b32_e32 v20, 64, v174
	v_add_u32_e32 v20, 64, v20
	v_cmp_lt_i32_e32 vcc, v19, v20
	s_nop 1
	v_cndmask_b32_e32 v19, v174, v19, vcc
	v_lshlrev_b32_e32 v19, 2, v19
	v_mov_b32_e32 v19, v18
	s_nop 1
	v_permlane16_swap_b32_e32 v19, v18
	s_waitcnt lgkmcnt(0)
	v_add_f32_e32 v18, v18, v19
	v_xor_b32_e32 v19, 32, v174
	v_cmp_lt_i32_e32 vcc, v19, v20
	s_nop 1
	v_cndmask_b32_e32 v19, v174, v19, vcc
	v_lshlrev_b32_e32 v19, 2, v19
	v_mov_b32_e32 v19, v18
	s_nop 1
	v_permlane32_swap_b32_e32 v19, v18
	s_waitcnt lgkmcnt(0)
	v_add_f32_e32 v18, v18, v19
	v_fmamk_f32 v18, v18, 0x3c800000, v172
	v_mul_f32_e32 v19, 0x4b800000, v18
	v_cmp_gt_f32_e32 vcc, s73, v18
	s_nop 1
	v_cndmask_b32_e32 v18, v18, v19, vcc
	v_rsq_f32_e32 v18, v18
	s_nop 0
	v_mul_f32_e32 v19, 0x45800000, v18
	v_cndmask_b32_e32 v18, v18, v19, vcc
	v_pk_mul_f32 v[12:13], v[12:13], v[18:19] op_sel_hi:[1,0]
	v_pk_mul_f32 v[14:15], v[14:15], v[18:19] op_sel_hi:[1,0]
	v_pk_mul_f32 v[8:9], v[8:9], v[18:19] op_sel_hi:[1,0]
	v_pk_mul_f32 v[10:11], v[10:11], v[18:19] op_sel_hi:[1,0]
	v_pk_mul_f32 v[4:5], v[4:5], v[18:19] op_sel_hi:[1,0]
	v_pk_mul_f32 v[6:7], v[6:7], v[18:19] op_sel_hi:[1,0]
	v_pk_mul_f32 v[0:1], v[0:1], v[18:19] op_sel_hi:[1,0]
	v_pk_mul_f32 v[2:3], v[2:3], v[18:19] op_sel_hi:[1,0]
	v_pk_mul_f32 v[14:15], v[160:161], v[14:15]
	v_pk_mul_f32 v[12:13], v[158:159], v[12:13]
	v_pk_mul_f32 v[10:11], v[156:157], v[10:11]
	v_pk_mul_f32 v[8:9], v[154:155], v[8:9]
	v_pk_mul_f32 v[6:7], v[152:153], v[6:7]
	v_pk_mul_f32 v[4:5], v[150:151], v[4:5]
	v_pk_mul_f32 v[2:3], v[148:149], v[2:3]
	v_pk_mul_f32 v[0:1], v[146:147], v[0:1]

; DI unsigned pk2(float a, float b) { f32x2 v = {a, b}; bf16v2_t r = __builtin_convertvector(v, bf16v2_t); return __builtin_bit_cast(unsigned, r); }
;     DI void operator()(const Acc& acc, const Unit& u, int wr, int wc, int fr, int fq, const float (&pre)[8]) const {
;     ...
;             for (int m = 0; m < 4; ++m) { const size_t row = (size_t)(row0 + ai * HALF + m * 16);
;                 const float rs = rsqrtf(pre[ai * 4 + m] * (1.f / DM) + EPS); float ss = 0.f;
; #pragma unroll
;                 for (int bj = 0; bj < 2; ++bj) { const f32x4 v0 = acc[ai][bj][m][0] * rs, v1 = acc[ai][bj][m][1] * rs;
;                     ss += v0[0] * v0[0] + v0[1] * v0[1] + v0[2] * v0[2] + v0[3] * v0[3] + v1[0] * v1[0] + v1[1] * v1[1] + v1[2] * v1[2] + v1[3] * v1[3];
;                     u32x4 w; w.x = pk2(v0[0], v0[1]); w.y = pk2(v0[2], v0[3]); w.z = pk2(v1[0], v1[1]); w.w = pk2(v1[2], v1[3]);
;                     const int col = col0 + bj * HALF;
;                     if (col < 1088) *(u32x4*)(lat + row * 1088 + col) = w;
;                     else if (col < 3136) *(u32x4*)(g + row * 2048 + (col - 1088)) = w; }
;                 if (u.pn < 4) { ss += __shfl_xor(ss, 16); ss += __shfl_xor(ss, 32); if (fq == 0) atomicAdd(ssql + (u.pn >> 1) * MTOK + row, ss); } }
.LBB0_1192:
	s_or_b64 exec, exec, s[14:15]
	s_cmp_lt_i32 s52, 4
	s_cselect_b64 s[50:51], -1, 0
	s_lshl_b32 s14, s52, 13
	s_and_b32 s48, s14, 0xffffc000
	s_ashr_i32 s49, s48, 31
	s_cmp_gt_i32 s52, 3
	s_cbranch_scc1 .LBB0_1196
	v_mul_f32_e32 v112, v153, v153
	v_mul_f32_e32 v113, v123, v123
	v_fmac_f32_e32 v112, v152, v152
	v_fmac_f32_e32 v113, v122, v122
	v_fmac_f32_e32 v112, v126, v126
	v_fmac_f32_e32 v113, v118, v118
	v_fmac_f32_e32 v112, v127, v127
	v_fmac_f32_e32 v113, v119, v119
	v_fmac_f32_e32 v112, v150, v150
	v_fmac_f32_e32 v113, v120, v120
	v_fmac_f32_e32 v112, v151, v151
	v_fmac_f32_e32 v113, v121, v121
	v_fmac_f32_e32 v112, v124, v124
	v_fmac_f32_e32 v113, v116, v116
	v_fmac_f32_e32 v112, v125, v125
	v_fmac_f32_e32 v113, v117, v117
	v_and_b32_e32 v114, 64, v167
	v_add_f32_e32 v112, v113, v112
	v_xor_b32_e32 v113, 16, v167
	v_add_u32_e32 v114, 64, v114
	v_cmp_lt_i32_e32 vcc, v113, v114
	s_nop 1
	v_cndmask_b32_e32 v113, v167, v113, vcc
	v_lshlrev_b32_e32 v113, 2, v113
	v_mov_b32_e32 v113, v112
	s_nop 1
	v_permlane16_swap_b32_e32 v113, v112
	s_waitcnt lgkmcnt(0)
	v_add_f32_e32 v112, v112, v113
	v_xor_b32_e32 v113, 32, v167
	v_cmp_lt_i32_e32 vcc, v113, v114
	s_nop 1
	v_cndmask_b32_e32 v113, v167, v113, vcc
	v_lshlrev_b32_e32 v113, 2, v113
	ds_bpermute_b32 v113, v113, v112
	s_and_saveexec_b64 s[14:15], s[6:7]
	s_cbranch_execz .LBB0_1195
	s_lshl_b64 s[52:53], s[48:49], 2
	s_add_u32 s52, s66, s52
	s_addc_u32 s53, s67, s53
	v_lshl_add_u64 v[114:115], v[146:147], 2, s[52:53]
	s_waitcnt lgkmcnt(0)
	v_add_f32_e32 v112, v112, v113
	flat_atomic_add_f32 v[114:115], v112

; DI unsigned pk2(float a, float b) { f32x2 v = {a, b}; bf16v2_t r = __builtin_convertvector(v, bf16v2_t); return __builtin_bit_cast(unsigned, r); }
;     DI void operator()(const Acc& acc, const Unit& u, int wr, int wc, int fr, int fq, const float (&pre)[8]) const {
;     ...
;                 for (int bj = 0; bj < 2; ++bj) { const f32x4 v0 = acc[ai][bj][m][0] * rs, v1 = acc[ai][bj][m][1] * rs;
;                     ss += v0[0] * v0[0] + v0[1] * v0[1] + v0[2] * v0[2] + v0[3] * v0[3] + v1[0] * v1[0] + v1[1] * v1[1] + v1[2] * v1[2] + v1[3] * v1[3];
;                     u32x4 w; w.x = pk2(v0[0], v0[1]); w.y = pk2(v0[2], v0[3]); w.z = pk2(v1[0], v1[1]); w.w = pk2(v1[2], v1[3]);
;                     const int col = col0 + bj * HALF;
;                     if (col < 1088) *(u32x4*)(lat + row * 1088 + col) = w;
;                     else if (col < 3136) *(u32x4*)(g + row * 2048 + (col - 1088)) = w; }
;                 if (u.pn < 4) { ss += __shfl_xor(ss, 16); ss += __shfl_xor(ss, 32); if (fq == 0) atomicAdd(ssql + (u.pn >> 1) * MTOK + row, ss); } }
.LBB0_1207:
	s_or_b64 exec, exec, s[14:15]
	s_nop 0
	v_cndmask_b32_e64 v96, 0, 1, s[50:51]
	v_cmp_ne_u32_e64 s[14:15], 1, v96
	s_andn2_b64 vcc, exec, s[50:51]
	s_cbranch_vccnz .LBB0_1211
	v_mul_f32_e32 v96, v115, v115
	v_mul_f32_e32 v97, v107, v107
	v_fmac_f32_e32 v96, v114, v114
	v_fmac_f32_e32 v97, v106, v106
	v_fmac_f32_e32 v96, v110, v110
	v_fmac_f32_e32 v97, v102, v102
	v_fmac_f32_e32 v96, v111, v111
	v_fmac_f32_e32 v97, v103, v103
	v_fmac_f32_e32 v96, v112, v112
	v_fmac_f32_e32 v97, v104, v104
	v_fmac_f32_e32 v96, v113, v113
	v_fmac_f32_e32 v97, v105, v105
	v_fmac_f32_e32 v96, v108, v108
	v_fmac_f32_e32 v97, v100, v100
	v_fmac_f32_e32 v96, v109, v109
	v_fmac_f32_e32 v97, v101, v101
	v_and_b32_e32 v98, 64, v167
	v_add_f32_e32 v96, v97, v96
	v_xor_b32_e32 v97, 16, v167
	v_add_u32_e32 v98, 64, v98
	v_cmp_lt_i32_e32 vcc, v97, v98
	s_nop 1
	v_cndmask_b32_e32 v97, v167, v97, vcc
	v_lshlrev_b32_e32 v97, 2, v97
	v_mov_b32_e32 v97, v96
	s_nop 1
	v_permlane16_swap_b32_e32 v97, v96
	s_waitcnt lgkmcnt(0)
	v_add_f32_e32 v96, v96, v97
	v_xor_b32_e32 v97, 32, v167
	v_cmp_lt_i32_e32 vcc, v97, v98
	s_nop 1
	v_cndmask_b32_e32 v97, v167, v97, vcc
	v_lshlrev_b32_e32 v97, 2, v97
	ds_bpermute_b32 v97, v97, v96
	s_and_saveexec_b64 s[50:51], s[6:7]
	s_cbranch_execz .LBB0_1210
	s_lshl_b64 s[52:53], s[48:49], 2
	s_add_u32 s52, s66, s52
	s_addc_u32 s53, s67, s53
	v_lshl_add_u64 v[98:99], v[146:147], 2, s[52:53]
	s_waitcnt lgkmcnt(0)
	v_add_f32_e32 v96, v96, v97
	flat_atomic_add_f32 v[98:99], v96 offset:64

; DI unsigned pk2(float a, float b) { f32x2 v = {a, b}; bf16v2_t r = __builtin_convertvector(v, bf16v2_t); return __builtin_bit_cast(unsigned, r); }
;     DI void operator()(const Acc& acc, const Unit& u, int wr, int wc, int fr, int fq, const float (&pre)[8]) const {
;     ...
;                 for (int bj = 0; bj < 2; ++bj) { const f32x4 v0 = acc[ai][bj][m][0] * rs, v1 = acc[ai][bj][m][1] * rs;
;                     ss += v0[0] * v0[0] + v0[1] * v0[1] + v0[2] * v0[2] + v0[3] * v0[3] + v1[0] * v1[0] + v1[1] * v1[1] + v1[2] * v1[2] + v1[3] * v1[3];
;                     u32x4 w; w.x = pk2(v0[0], v0[1]); w.y = pk2(v0[2], v0[3]); w.z = pk2(v1[0], v1[1]); w.w = pk2(v1[2], v1[3]);
;                     const int col = col0 + bj * HALF;
;                     if (col < 1088) *(u32x4*)(lat + row * 1088 + col) = w;
;                     else if (col < 3136) *(u32x4*)(g + row * 2048 + (col - 1088)) = w; }
;                 if (u.pn < 4) { ss += __shfl_xor(ss, 16); ss += __shfl_xor(ss, 32); if (fq == 0) atomicAdd(ssql + (u.pn >> 1) * MTOK + row, ss); } }
.LBB0_1223:
	v_mul_f32_e32 v80, v99, v99
	v_mul_f32_e32 v81, v91, v91
	v_fmac_f32_e32 v80, v98, v98
	v_fmac_f32_e32 v81, v90, v90
	v_fmac_f32_e32 v80, v94, v94
	v_fmac_f32_e32 v81, v86, v86
	v_fmac_f32_e32 v80, v95, v95
	v_fmac_f32_e32 v81, v87, v87
	v_fmac_f32_e32 v80, v96, v96
	v_fmac_f32_e32 v81, v88, v88
	v_fmac_f32_e32 v80, v97, v97
	v_fmac_f32_e32 v81, v89, v89
	v_fmac_f32_e32 v80, v92, v92
	v_fmac_f32_e32 v81, v84, v84
	v_fmac_f32_e32 v80, v93, v93
	v_fmac_f32_e32 v81, v85, v85
	v_and_b32_e32 v82, 64, v167
	v_add_f32_e32 v80, v81, v80
	v_xor_b32_e32 v81, 16, v167
	v_add_u32_e32 v82, 64, v82
	v_cmp_lt_i32_e32 vcc, v81, v82
	s_nop 1
	v_cndmask_b32_e32 v81, v167, v81, vcc
	v_lshlrev_b32_e32 v81, 2, v81
	v_mov_b32_e32 v81, v80
	s_nop 1
	v_permlane16_swap_b32_e32 v81, v80
	s_waitcnt lgkmcnt(0)
	v_add_f32_e32 v80, v80, v81
	v_xor_b32_e32 v81, 32, v167
	v_cmp_lt_i32_e32 vcc, v81, v82
	s_nop 1
	v_cndmask_b32_e32 v81, v167, v81, vcc
	v_lshlrev_b32_e32 v81, 2, v81
	ds_bpermute_b32 v81, v81, v80
	s_and_saveexec_b64 s[50:51], s[6:7]
	s_cbranch_execz .LBB0_1225
	s_lshl_b64 s[52:53], s[48:49], 2
	s_add_u32 s52, s66, s52
	s_addc_u32 s53, s67, s53
	v_lshl_add_u64 v[82:83], v[146:147], 2, s[52:53]
	s_waitcnt lgkmcnt(0)
	v_add_f32_e32 v80, v80, v81
	flat_atomic_add_f32 v[82:83], v80 offset:128

; DI unsigned pk2(float a, float b) { f32x2 v = {a, b}; bf16v2_t r = __builtin_convertvector(v, bf16v2_t); return __builtin_bit_cast(unsigned, r); }
;     DI void operator()(const Acc& acc, const Unit& u, int wr, int wc, int fr, int fq, const float (&pre)[8]) const {
;     ...
;                 for (int bj = 0; bj < 2; ++bj) { const f32x4 v0 = acc[ai][bj][m][0] * rs, v1 = acc[ai][bj][m][1] * rs;
;                     ss += v0[0] * v0[0] + v0[1] * v0[1] + v0[2] * v0[2] + v0[3] * v0[3] + v1[0] * v1[0] + v1[1] * v1[1] + v1[2] * v1[2] + v1[3] * v1[3];
;                     u32x4 w; w.x = pk2(v0[0], v0[1]); w.y = pk2(v0[2], v0[3]); w.z = pk2(v1[0], v1[1]); w.w = pk2(v1[2], v1[3]);
;                     const int col = col0 + bj * HALF;
;                     if (col < 1088) *(u32x4*)(lat + row * 1088 + col) = w;
;                     else if (col < 3136) *(u32x4*)(g + row * 2048 + (col - 1088)) = w; }
;                 if (u.pn < 4) { ss += __shfl_xor(ss, 16); ss += __shfl_xor(ss, 32); if (fq == 0) atomicAdd(ssql + (u.pn >> 1) * MTOK + row, ss); } }
.LBB0_1238:
	v_mul_f32_e32 v64, v83, v83
	v_mul_f32_e32 v65, v75, v75
	v_fmac_f32_e32 v64, v82, v82
	v_fmac_f32_e32 v65, v74, v74
	v_fmac_f32_e32 v64, v78, v78
	v_fmac_f32_e32 v65, v70, v70
	v_fmac_f32_e32 v64, v79, v79
	v_fmac_f32_e32 v65, v71, v71
	v_fmac_f32_e32 v64, v80, v80
	v_fmac_f32_e32 v65, v72, v72
	v_fmac_f32_e32 v64, v81, v81
	v_fmac_f32_e32 v65, v73, v73
	v_fmac_f32_e32 v64, v76, v76
	v_fmac_f32_e32 v65, v68, v68
	v_fmac_f32_e32 v64, v77, v77
	v_fmac_f32_e32 v65, v69, v69
	v_and_b32_e32 v66, 64, v167
	v_add_f32_e32 v64, v65, v64
	v_xor_b32_e32 v65, 16, v167
	v_add_u32_e32 v66, 64, v66
	v_cmp_lt_i32_e32 vcc, v65, v66
	s_nop 1
	v_cndmask_b32_e32 v65, v167, v65, vcc
	v_lshlrev_b32_e32 v65, 2, v65
	v_mov_b32_e32 v65, v64
	s_nop 1
	v_permlane16_swap_b32_e32 v65, v64
	s_waitcnt lgkmcnt(0)
	v_add_f32_e32 v64, v64, v65
	v_xor_b32_e32 v65, 32, v167
	v_cmp_lt_i32_e32 vcc, v65, v66
	s_nop 1
	v_cndmask_b32_e32 v65, v167, v65, vcc
	v_lshlrev_b32_e32 v65, 2, v65
	ds_bpermute_b32 v65, v65, v64
	s_and_saveexec_b64 s[50:51], s[6:7]
	s_cbranch_execz .LBB0_1240
	s_lshl_b64 s[52:53], s[48:49], 2
	s_add_u32 s52, s66, s52
	s_addc_u32 s53, s67, s53
	v_lshl_add_u64 v[66:67], v[146:147], 2, s[52:53]
	s_waitcnt lgkmcnt(0)
	v_add_f32_e32 v64, v64, v65
	flat_atomic_add_f32 v[66:67], v64 offset:192

; DI unsigned pk2(float a, float b) { f32x2 v = {a, b}; bf16v2_t r = __builtin_convertvector(v, bf16v2_t); return __builtin_bit_cast(unsigned, r); }
;     DI void operator()(const Acc& acc, const Unit& u, int wr, int wc, int fr, int fq, const float (&pre)[8]) const {
;     ...
;                 for (int bj = 0; bj < 2; ++bj) { const f32x4 v0 = acc[ai][bj][m][0] * rs, v1 = acc[ai][bj][m][1] * rs;
;                     ss += v0[0] * v0[0] + v0[1] * v0[1] + v0[2] * v0[2] + v0[3] * v0[3] + v1[0] * v1[0] + v1[1] * v1[1] + v1[2] * v1[2] + v1[3] * v1[3];
;                     u32x4 w; w.x = pk2(v0[0], v0[1]); w.y = pk2(v0[2], v0[3]); w.z = pk2(v1[0], v1[1]); w.w = pk2(v1[2], v1[3]);
;                     const int col = col0 + bj * HALF;
;                     if (col < 1088) *(u32x4*)(lat + row * 1088 + col) = w;
;                     else if (col < 3136) *(u32x4*)(g + row * 2048 + (col - 1088)) = w; }
;                 if (u.pn < 4) { ss += __shfl_xor(ss, 16); ss += __shfl_xor(ss, 32); if (fq == 0) atomicAdd(ssql + (u.pn >> 1) * MTOK + row, ss); } }
.LBB0_1253:
	v_mul_f32_e32 v48, v67, v67
	v_mul_f32_e32 v49, v59, v59
	v_fmac_f32_e32 v48, v66, v66
	v_fmac_f32_e32 v49, v58, v58
	v_fmac_f32_e32 v48, v62, v62
	v_fmac_f32_e32 v49, v54, v54
	v_fmac_f32_e32 v48, v63, v63
	v_fmac_f32_e32 v49, v55, v55
	v_fmac_f32_e32 v48, v64, v64
	v_fmac_f32_e32 v49, v56, v56
	v_fmac_f32_e32 v48, v65, v65
	v_fmac_f32_e32 v49, v57, v57
	v_fmac_f32_e32 v48, v60, v60
	v_fmac_f32_e32 v49, v52, v52
	v_fmac_f32_e32 v48, v61, v61
	v_fmac_f32_e32 v49, v53, v53
	v_and_b32_e32 v50, 64, v167
	v_add_f32_e32 v48, v49, v48
	v_xor_b32_e32 v49, 16, v167
	v_add_u32_e32 v50, 64, v50
	v_cmp_lt_i32_e32 vcc, v49, v50
	s_nop 1
	v_cndmask_b32_e32 v49, v167, v49, vcc
	v_lshlrev_b32_e32 v49, 2, v49
	v_mov_b32_e32 v49, v48
	s_nop 1
	v_permlane16_swap_b32_e32 v49, v48
	s_waitcnt lgkmcnt(0)
	v_add_f32_e32 v48, v48, v49
	v_xor_b32_e32 v49, 32, v167
	v_cmp_lt_i32_e32 vcc, v49, v50
	s_nop 1
	v_cndmask_b32_e32 v49, v167, v49, vcc
	v_lshlrev_b32_e32 v49, 2, v49
	ds_bpermute_b32 v49, v49, v48
	s_and_saveexec_b64 s[50:51], s[6:7]
	s_cbranch_execz .LBB0_1255
	s_lshl_b64 s[52:53], s[48:49], 2
	s_add_u32 s52, s66, s52
	s_addc_u32 s53, s67, s53
	v_lshl_add_u64 v[50:51], v[146:147], 2, s[52:53]
	s_waitcnt lgkmcnt(0)
	v_add_f32_e32 v48, v48, v49
	flat_atomic_add_f32 v[50:51], v48 offset:512

; DI unsigned pk2(float a, float b) { f32x2 v = {a, b}; bf16v2_t r = __builtin_convertvector(v, bf16v2_t); return __builtin_bit_cast(unsigned, r); }
;     DI void operator()(const Acc& acc, const Unit& u, int wr, int wc, int fr, int fq, const float (&pre)[8]) const {
;     ...
;                 for (int bj = 0; bj < 2; ++bj) { const f32x4 v0 = acc[ai][bj][m][0] * rs, v1 = acc[ai][bj][m][1] * rs;
;                     ss += v0[0] * v0[0] + v0[1] * v0[1] + v0[2] * v0[2] + v0[3] * v0[3] + v1[0] * v1[0] + v1[1] * v1[1] + v1[2] * v1[2] + v1[3] * v1[3];
;                     u32x4 w; w.x = pk2(v0[0], v0[1]); w.y = pk2(v0[2], v0[3]); w.z = pk2(v1[0], v1[1]); w.w = pk2(v1[2], v1[3]);
;                     const int col = col0 + bj * HALF;
;                     if (col < 1088) *(u32x4*)(lat + row * 1088 + col) = w;
;                     else if (col < 3136) *(u32x4*)(g + row * 2048 + (col - 1088)) = w; }
;                 if (u.pn < 4) { ss += __shfl_xor(ss, 16); ss += __shfl_xor(ss, 32); if (fq == 0) atomicAdd(ssql + (u.pn >> 1) * MTOK + row, ss); } }
.LBB0_1268:
	v_mul_f32_e32 v32, v51, v51
	v_mul_f32_e32 v33, v43, v43
	v_fmac_f32_e32 v32, v50, v50
	v_fmac_f32_e32 v33, v42, v42
	v_fmac_f32_e32 v32, v46, v46
	v_fmac_f32_e32 v33, v38, v38
	v_fmac_f32_e32 v32, v47, v47
	v_fmac_f32_e32 v33, v39, v39
	v_fmac_f32_e32 v32, v48, v48
	v_fmac_f32_e32 v33, v40, v40
	v_fmac_f32_e32 v32, v49, v49
	v_fmac_f32_e32 v33, v41, v41
	v_fmac_f32_e32 v32, v44, v44
	v_fmac_f32_e32 v33, v36, v36
	v_fmac_f32_e32 v32, v45, v45
	v_fmac_f32_e32 v33, v37, v37
	v_and_b32_e32 v34, 64, v167
	v_add_f32_e32 v32, v33, v32
	v_xor_b32_e32 v33, 16, v167
	v_add_u32_e32 v34, 64, v34
	v_cmp_lt_i32_e32 vcc, v33, v34
	s_nop 1
	v_cndmask_b32_e32 v33, v167, v33, vcc
	v_lshlrev_b32_e32 v33, 2, v33
	v_mov_b32_e32 v33, v32
	s_nop 1
	v_permlane16_swap_b32_e32 v33, v32
	s_waitcnt lgkmcnt(0)
	v_add_f32_e32 v32, v32, v33
	v_xor_b32_e32 v33, 32, v167
	v_cmp_lt_i32_e32 vcc, v33, v34
	s_nop 1
	v_cndmask_b32_e32 v33, v167, v33, vcc
	v_lshlrev_b32_e32 v33, 2, v33
	ds_bpermute_b32 v33, v33, v32
	s_and_saveexec_b64 s[50:51], s[6:7]
	s_cbranch_execz .LBB0_1270
	s_lshl_b64 s[52:53], s[48:49], 2
	s_add_u32 s52, s66, s52
	s_addc_u32 s53, s67, s53
	v_lshl_add_u64 v[34:35], v[146:147], 2, s[52:53]
	s_waitcnt lgkmcnt(0)
	v_add_f32_e32 v32, v32, v33
	flat_atomic_add_f32 v[34:35], v32 offset:576

; DI unsigned pk2(float a, float b) { f32x2 v = {a, b}; bf16v2_t r = __builtin_convertvector(v, bf16v2_t); return __builtin_bit_cast(unsigned, r); }
;     DI void operator()(const Acc& acc, const Unit& u, int wr, int wc, int fr, int fq, const float (&pre)[8]) const {
;     ...
;                 for (int bj = 0; bj < 2; ++bj) { const f32x4 v0 = acc[ai][bj][m][0] * rs, v1 = acc[ai][bj][m][1] * rs;
;                     ss += v0[0] * v0[0] + v0[1] * v0[1] + v0[2] * v0[2] + v0[3] * v0[3] + v1[0] * v1[0] + v1[1] * v1[1] + v1[2] * v1[2] + v1[3] * v1[3];
;                     u32x4 w; w.x = pk2(v0[0], v0[1]); w.y = pk2(v0[2], v0[3]); w.z = pk2(v1[0], v1[1]); w.w = pk2(v1[2], v1[3]);
;                     const int col = col0 + bj * HALF;
;                     if (col < 1088) *(u32x4*)(lat + row * 1088 + col) = w;
;                     else if (col < 3136) *(u32x4*)(g + row * 2048 + (col - 1088)) = w; }
;                 if (u.pn < 4) { ss += __shfl_xor(ss, 16); ss += __shfl_xor(ss, 32); if (fq == 0) atomicAdd(ssql + (u.pn >> 1) * MTOK + row, ss); } }
.LBB0_1283:
	v_mul_f32_e32 v16, v35, v35
	v_mul_f32_e32 v17, v27, v27
	v_fmac_f32_e32 v16, v34, v34
	v_fmac_f32_e32 v17, v26, v26
	v_fmac_f32_e32 v16, v30, v30
	v_fmac_f32_e32 v17, v22, v22
	v_fmac_f32_e32 v16, v31, v31
	v_fmac_f32_e32 v17, v23, v23
	v_fmac_f32_e32 v16, v32, v32
	v_fmac_f32_e32 v17, v24, v24
	v_fmac_f32_e32 v16, v33, v33
	v_fmac_f32_e32 v17, v25, v25
	v_fmac_f32_e32 v16, v28, v28
	v_fmac_f32_e32 v17, v20, v20
	v_fmac_f32_e32 v16, v29, v29
	v_fmac_f32_e32 v17, v21, v21
	v_and_b32_e32 v18, 64, v167
	v_add_f32_e32 v16, v17, v16
	v_xor_b32_e32 v17, 16, v167
	v_add_u32_e32 v18, 64, v18
	v_cmp_lt_i32_e32 vcc, v17, v18
	s_nop 1
	v_cndmask_b32_e32 v17, v167, v17, vcc
	v_lshlrev_b32_e32 v17, 2, v17
	v_mov_b32_e32 v17, v16
	s_nop 1
	v_permlane16_swap_b32_e32 v17, v16
	s_waitcnt lgkmcnt(0)
	v_add_f32_e32 v16, v16, v17
	v_xor_b32_e32 v17, 32, v167
	v_cmp_lt_i32_e32 vcc, v17, v18
	s_nop 1
	v_cndmask_b32_e32 v17, v167, v17, vcc
	v_lshlrev_b32_e32 v17, 2, v17
	ds_bpermute_b32 v17, v17, v16
	s_and_saveexec_b64 s[50:51], s[6:7]
	s_cbranch_execz .LBB0_1285
	s_lshl_b64 s[52:53], s[48:49], 2
	s_add_u32 s52, s66, s52
	s_addc_u32 s53, s67, s53
	v_lshl_add_u64 v[18:19], v[146:147], 2, s[52:53]
	s_waitcnt lgkmcnt(0)
	v_add_f32_e32 v16, v16, v17
	flat_atomic_add_f32 v[18:19], v16 offset:640

; DI unsigned pk2(float a, float b) { f32x2 v = {a, b}; bf16v2_t r = __builtin_convertvector(v, bf16v2_t); return __builtin_bit_cast(unsigned, r); }
;     DI void operator()(const Acc& acc, const Unit& u, int wr, int wc, int fr, int fq, const float (&pre)[8]) const {
;     ...
;                 for (int bj = 0; bj < 2; ++bj) { const f32x4 v0 = acc[ai][bj][m][0] * rs, v1 = acc[ai][bj][m][1] * rs;
;                     ss += v0[0] * v0[0] + v0[1] * v0[1] + v0[2] * v0[2] + v0[3] * v0[3] + v1[0] * v1[0] + v1[1] * v1[1] + v1[2] * v1[2] + v1[3] * v1[3];
;                     u32x4 w; w.x = pk2(v0[0], v0[1]); w.y = pk2(v0[2], v0[3]); w.z = pk2(v1[0], v1[1]); w.w = pk2(v1[2], v1[3]);
;                     const int col = col0 + bj * HALF;
;                     if (col < 1088) *(u32x4*)(lat + row * 1088 + col) = w;
;                     else if (col < 3136) *(u32x4*)(g + row * 2048 + (col - 1088)) = w; }
;                 if (u.pn < 4) { ss += __shfl_xor(ss, 16); ss += __shfl_xor(ss, 32); if (fq == 0) atomicAdd(ssql + (u.pn >> 1) * MTOK + row, ss); } }
.LBB0_1299:
	v_mul_f32_e32 v0, v19, v19
	v_mul_f32_e32 v1, v11, v11
	v_fmac_f32_e32 v0, v18, v18
	v_fmac_f32_e32 v1, v10, v10
	v_fmac_f32_e32 v0, v14, v14
	v_fmac_f32_e32 v1, v6, v6
	v_fmac_f32_e32 v0, v15, v15
	v_fmac_f32_e32 v1, v7, v7
	v_fmac_f32_e32 v0, v16, v16
	v_fmac_f32_e32 v1, v8, v8
	v_fmac_f32_e32 v0, v17, v17
	v_fmac_f32_e32 v1, v9, v9
	v_fmac_f32_e32 v0, v12, v12
	v_fmac_f32_e32 v1, v4, v4
	v_fmac_f32_e32 v0, v13, v13
	v_fmac_f32_e32 v1, v5, v5
	v_and_b32_e32 v2, 64, v167
	v_add_f32_e32 v0, v1, v0
	v_xor_b32_e32 v1, 16, v167
	v_add_u32_e32 v2, 64, v2
	v_cmp_lt_i32_e32 vcc, v1, v2
	s_nop 1
	v_cndmask_b32_e32 v1, v167, v1, vcc
	v_lshlrev_b32_e32 v1, 2, v1
	v_mov_b32_e32 v1, v0
	s_nop 1
	v_permlane16_swap_b32_e32 v1, v0
	s_waitcnt lgkmcnt(0)
	v_add_f32_e32 v0, v0, v1
	v_xor_b32_e32 v1, 32, v167
	v_cmp_lt_i32_e32 vcc, v1, v2
	s_nop 1
	v_cndmask_b32_e32 v1, v167, v1, vcc
	v_lshlrev_b32_e32 v1, 2, v1
	ds_bpermute_b32 v1, v1, v0
	s_and_saveexec_b64 s[10:11], s[6:7]
	s_cbranch_execz .LBB0_1301
	s_lshl_b64 s[12:13], s[48:49], 2
	s_add_u32 s12, s66, s12
	s_addc_u32 s13, s67, s13
	v_lshl_add_u64 v[2:3], v[146:147], 2, s[12:13]
	s_waitcnt lgkmcnt(0)
	v_add_f32_e32 v0, v0, v1
	flat_atomic_add_f32 v[2:3], v0 offset:704
